# phase 0 adaLN: conditioning-vector loads issued together before the SiLU staging (on top of the batched GEMV loads)
# speedup vs baseline: 1.0578x; 1.0019x over previous
.LBB0_73:
	s_andn2_b64 vcc, exec, s[4:5]
	s_cbranch_vccnz .LBB0_86
	v_mov_b32_e32 v1, v228
	s_movk_i32 s0, 0xc00
	s_nop 0
	v_cmp_gt_i32_e32 vcc, s0, v1
	v_lshlrev_b32_e32 v22, 2, v1
	s_barrier
	s_and_saveexec_b64 s[4:5], vcc
	s_cbranch_execz .LBB0_81
	v_readlane_b32 s36, v252, 13
	v_readlane_b32 s37, v252, 14
	s_add_u32 s10, s60, 0x1000
	s_addc_u32 s11, s61, 0
	s_nop 2
	global_load_dword v40, v22, s[36:37]
	global_load_dword v41, v22, s[36:37] offset:1024
	global_load_dword v42, v22, s[36:37] offset:2048
	global_load_dword v43, v22, s[36:37] offset:3072
	global_load_dword v44, v22, s[60:61]
	global_load_dword v45, v22, s[60:61] offset:1024
	global_load_dword v46, v22, s[60:61] offset:2048
	global_load_dword v47, v22, s[60:61] offset:3072
	global_load_dword v48, v22, s[10:11]
	global_load_dword v49, v22, s[10:11] offset:1024
	global_load_dword v50, v22, s[10:11] offset:2048
	global_load_dword v51, v22, s[10:11] offset:3072
	s_waitcnt vmcnt(11)
	v_mul_f32_e32 v52, 0xbfb8aa3b, v40
	v_exp_f32_e32 v52, v52
	s_nop 0
	v_add_f32_e32 v52, 1.0, v52
	v_rcp_f32_e32 v52, v52
	s_nop 0
	v_mul_f32_e32 v40, v40, v52
	ds_write_b32 v22, v40
	s_waitcnt vmcnt(10)
	v_mul_f32_e32 v52, 0xbfb8aa3b, v41
	v_exp_f32_e32 v52, v52
	s_nop 0
	v_add_f32_e32 v52, 1.0, v52
	v_rcp_f32_e32 v52, v52
	s_nop 0
	v_mul_f32_e32 v41, v41, v52
	ds_write_b32 v22, v41 offset:1024
	s_waitcnt vmcnt(9)
	v_mul_f32_e32 v52, 0xbfb8aa3b, v42
	v_exp_f32_e32 v52, v52
	s_nop 0
	v_add_f32_e32 v52, 1.0, v52
	v_rcp_f32_e32 v52, v52
	s_nop 0
	v_mul_f32_e32 v42, v42, v52
	ds_write_b32 v22, v42 offset:2048
	s_waitcnt vmcnt(8)
	v_mul_f32_e32 v52, 0xbfb8aa3b, v43
	v_exp_f32_e32 v52, v52
	s_nop 0
	v_add_f32_e32 v52, 1.0, v52
	v_rcp_f32_e32 v52, v52
	s_nop 0
	v_mul_f32_e32 v43, v43, v52
	ds_write_b32 v22, v43 offset:3072
	s_waitcnt vmcnt(7)
	v_mul_f32_e32 v52, 0xbfb8aa3b, v44
	v_exp_f32_e32 v52, v52
	s_nop 0
	v_add_f32_e32 v52, 1.0, v52
	v_rcp_f32_e32 v52, v52
	s_nop 0
	v_mul_f32_e32 v44, v44, v52
	ds_write_b32 v22, v44 offset:4096
	s_waitcnt vmcnt(6)
	v_mul_f32_e32 v52, 0xbfb8aa3b, v45
	v_exp_f32_e32 v52, v52
	s_nop 0
	v_add_f32_e32 v52, 1.0, v52
	v_rcp_f32_e32 v52, v52
	s_nop 0
	v_mul_f32_e32 v45, v45, v52
	ds_write_b32 v22, v45 offset:5120
	s_waitcnt vmcnt(5)
	v_mul_f32_e32 v52, 0xbfb8aa3b, v46
	v_exp_f32_e32 v52, v52
	s_nop 0
	v_add_f32_e32 v52, 1.0, v52
	v_rcp_f32_e32 v52, v52
	s_nop 0
	v_mul_f32_e32 v46, v46, v52
	ds_write_b32 v22, v46 offset:6144
	s_waitcnt vmcnt(4)
	v_mul_f32_e32 v52, 0xbfb8aa3b, v47
	v_exp_f32_e32 v52, v52
	s_nop 0
	v_add_f32_e32 v52, 1.0, v52
	v_rcp_f32_e32 v52, v52
	s_nop 0
	v_mul_f32_e32 v47, v47, v52
	ds_write_b32 v22, v47 offset:7168
	s_waitcnt vmcnt(3)
	v_mul_f32_e32 v52, 0xbfb8aa3b, v48
	v_exp_f32_e32 v52, v52
	s_nop 0
	v_add_f32_e32 v52, 1.0, v52
	v_rcp_f32_e32 v52, v52
	s_nop 0
	v_mul_f32_e32 v48, v48, v52
	ds_write_b32 v22, v48 offset:8192
	s_waitcnt vmcnt(2)
	v_mul_f32_e32 v52, 0xbfb8aa3b, v49
	v_exp_f32_e32 v52, v52
	s_nop 0
	v_add_f32_e32 v52, 1.0, v52
	v_rcp_f32_e32 v52, v52
	s_nop 0
	v_mul_f32_e32 v49, v49, v52
	ds_write_b32 v22, v49 offset:9216
	s_waitcnt vmcnt(1)
	v_mul_f32_e32 v52, 0xbfb8aa3b, v50
	v_exp_f32_e32 v52, v52
	s_nop 0
	v_add_f32_e32 v52, 1.0, v52
	v_rcp_f32_e32 v52, v52
	s_nop 0
	v_mul_f32_e32 v50, v50, v52
	ds_write_b32 v22, v50 offset:10240
	s_waitcnt vmcnt(0)
	v_mul_f32_e32 v52, 0xbfb8aa3b, v51
	v_exp_f32_e32 v52, v52
	s_nop 0
	v_add_f32_e32 v52, 1.0, v52
	v_rcp_f32_e32 v52, v52
	s_nop 0
	v_mul_f32_e32 v51, v51, v52
	ds_write_b32 v22, v51 offset:11264
	v_readlane_b32 s38, v252, 15
	v_readlane_b32 s39, v252, 16
	v_readlane_b32 s40, v252, 17
	v_readlane_b32 s41, v252, 18
	v_readlane_b32 s42, v252, 19
	v_readlane_b32 s43, v252, 20
	v_readlane_b32 s44, v252, 21
	v_readlane_b32 s45, v252, 22
	v_readlane_b32 s46, v252, 23
	v_readlane_b32 s47, v252, 24
	v_readlane_b32 s48, v252, 25
	v_readlane_b32 s49, v252, 26
	v_readlane_b32 s50, v252, 27
	v_readlane_b32 s51, v252, 28
